# per-chunk state scratch in 16-byte-unit layout too; XCD-local barriers now guarded by a runtime check that block-id%8 maps one-to-one onto XCC ids (falls back to full grid barriers otherwise)
# baseline (speedup 1.0000x reference)
.LBB0_17:
	s_or_b64 exec, exec, s[4:5]
	s_waitcnt lgkmcnt(0)
	s_barrier
	s_add_u32 s94, s58, 0xfd29000
	s_getreg_b32 s0, hwreg(HW_REG_XCC_ID, 0, 4)
	s_addc_u32 s95, s59, 0
	s_and_b32 s3, s0, 15
	v_readlane_b32 s0, v255, 1
	v_readlane_b32 s1, v255, 2
	s_and_saveexec_b64 s[4:5], s[0:1]
	s_cbranch_execz .LBB0_20
	s_mov_b64 s[6:7], exec
	v_mbcnt_lo_u32_b32 v0, s6, 0
	v_mbcnt_hi_u32_b32 v0, s7, v0
	v_cmp_eq_u32_e32 vcc, 0, v0
	s_and_b64 s[8:9], exec, vcc
	s_mov_b64 exec, s[8:9]
	s_cbranch_execz .LBB0_20
	s_lshl_b32 s0, s3, 8
	s_bcnt1_i32_b64 s1, s[6:7]
	v_mov_b32_e32 v0, s0
	v_mov_b32_e32 v1, s1
	global_atomic_add v0, v1, s[94:95] offset:1024
	s_and_b32 s0, s76, 7
	s_lshl_b32 s0, s0, 2
	s_lshl_b32 s1, 1, s3
	v_mov_b32_e32 v0, s0
	v_mov_b32_e32 v1, s1
	global_atomic_or v0, v1, s[94:95] offset:544

.LBB0_91:
	s_or_b64 exec, exec, s[4:5]
	s_cmpk_gt_i32 s76, 0x25f
	s_waitcnt lgkmcnt(0)
	s_barrier
	v_mov_b32_e32 v0, 0
	global_load_dword v1, v0, s[94:95] offset:544 sc1
	global_load_dword v2, v0, s[94:95] offset:548 sc1
	global_load_dword v3, v0, s[94:95] offset:552 sc1
	global_load_dword v4, v0, s[94:95] offset:556 sc1
	global_load_dword v5, v0, s[94:95] offset:560 sc1
	global_load_dword v6, v0, s[94:95] offset:564 sc1
	global_load_dword v7, v0, s[94:95] offset:568 sc1
	global_load_dword v8, v0, s[94:95] offset:572 sc1
	s_waitcnt vmcnt(0)
	v_or3_b32 v9, v1, v2, v3
	v_or3_b32 v9, v9, v4, v5
	v_or3_b32 v9, v9, v6, v7
	v_or_b32_e32 v9, v9, v8
	v_bcnt_u32_b32 v10, v1, 0
	v_bcnt_u32_b32 v10, v2, v10
	v_bcnt_u32_b32 v10, v3, v10
	v_bcnt_u32_b32 v10, v4, v10
	v_bcnt_u32_b32 v10, v5, v10
	v_bcnt_u32_b32 v10, v6, v10
	v_bcnt_u32_b32 v10, v7, v10
	v_bcnt_u32_b32 v10, v8, v10
	v_cmp_eq_u32_e32 vcc, 8, v10
	s_nop 1
	v_cndmask_b32_e64 v10, 0, 1, vcc
	v_cmp_eq_u32_e32 vcc, 0xff, v9
	s_nop 1
	v_cndmask_b32_e32 v10, 0, v10, vcc
	s_nop 0
	v_readfirstlane_b32 s0, v10
	s_nop 3
	v_writelane_b32 v255, s0, 11
	s_cmpk_gt_i32 s76, 0x25f
	s_cbranch_scc1 .LBB0_100
	s_add_u32 s24, s58, 0xa50000
	s_addc_u32 s25, s59, 0
	s_add_u32 s28, s58, 0xfd11000
	v_mbcnt_lo_u32_b32 v0, -1, 0
	s_addc_u32 s29, s59, 0
	v_mbcnt_hi_u32_b32 v49, -1, v0
	s_add_u32 s30, s58, 0xcd1000
	v_and_b32_e32 v0, 64, v49
	s_addc_u32 s31, s59, 0
	s_mov_b32 s2, 0x2aaaaaab
	s_movk_i32 s33, 0x3000
	s_movk_i32 s37, 0xc00
	s_mov_b64 s[34:35], 0x1000
	s_movk_i32 s39, 0x1000
	v_mov_b32_e32 v33, 0
	s_mov_b32 s36, 0x3a800000
	s_mov_b32 s38, 0x358637bd
	s_mov_b32 s62, 0x800000
	v_mov_b32_e32 v48, 9
	v_add_u32_e32 v50, 64, v0
	v_xor_b32_e32 v51, 32, v49
	v_xor_b32_e32 v52, 16, v49
	v_xor_b32_e32 v53, 8, v49
	v_xor_b32_e32 v54, 4, v49
	v_xor_b32_e32 v55, 2, v49
	v_xor_b32_e32 v56, 1, v49
	s_mov_b32 s63, s76
	s_branch .LBB0_94

.LBB0_132:
	s_andn2_saveexec_b64 s[8:9], s[8:9]
	s_cbranch_execz .LBB0_152
	s_mov_b64 s[8:9], exec
	v_readlane_b32 s98, v255, 11
	s_nop 0
	s_cmp_lg_u32 s98, 0
	s_cbranch_scc1 .LBB0_149
	buffer_wbl2 sc1
	s_waitcnt lgkmcnt(0)
	s_waitcnt vmcnt(0)
	v_mbcnt_lo_u32_b32 v1, s8, 0
	v_mbcnt_hi_u32_b32 v1, s9, v1
	v_cmp_eq_u32_e32 vcc, 0, v1
	s_and_saveexec_b64 s[10:11], vcc
	s_cbranch_execz .LBB0_135
	s_bcnt1_i32_b64 s0, s[8:9]
	v_mov_b32_e32 v2, 0xfd2c000
	v_mov_b32_e32 v3, s0
	global_atomic_add v2, v2, v3, s[58:59] offset:1024 sc0

.LBB0_412:
	s_or_b64 exec, exec, s[66:67]
	s_waitcnt lgkmcnt(0)
	v_add_f32_e32 v0, v1, v0
	s_lshl_b32 s0, s79, 2
	v_mul_f32_e32 v0, 0x3fb8aa3b, v0
	s_and_b32 s36, s0, 0xffffff00
	s_lshl_b64 s[0:1], s[4:5], 14
	v_exp_f32_e32 v0, v0
	s_add_u32 s24, s84, s0
	s_addc_u32 s25, s85, s1
	s_add_u32 s0, s82, s0
	v_lshl_or_b32 v1, v55, 2, s36
	s_addc_u32 s1, s83, s1
	v_lshlrev_b32_e32 v204, 1, v54
	ds_write_b32 v1, v0 offset:8192
	v_lshl_add_u64 v[0:1], s[0:1], 0, v[204:205]
	v_lshlrev_b32_e32 v2, 7, v206
	v_mov_b32_e32 v3, v205
	v_lshl_add_u64 v[16:17], v[0:1], 0, v[2:3]
	v_lshl_add_u64 v[20:21], s[24:25], 0, v[204:205]
	s_mov_b32 s98, s24
	s_mov_b32 s99, s25
	s_mov_b32 s100, s0
	s_mov_b32 s101, s1
	v_and_b32_e32 v226, 3, v206
	v_lshlrev_b32_e32 v226, 9, v226
	v_lshrrev_b32_e32 v227, 2, v206
	v_lshl_or_b32 v226, v227, 4, v226
	v_lshl_or_b32 v226, v56, 11, v226
	v_add_u32_e32 v227, 0x1000, v226
	v_add_u32_e32 v228, 0x2000, v226
	v_add_u32_e32 v229, 0x3000, v226
	s_waitcnt lgkmcnt(0)
	s_barrier
	global_load_dwordx4 v[4:7], v226, s[100:101]
	global_load_dwordx4 v[8:11], v227, s[100:101]
	v_lshl_add_u64 v[22:23], v[20:21], 0, v[2:3]
	global_load_dwordx4 v[120:123], v226, s[98:99]
	global_load_dwordx4 v[12:15], v228, s[100:101]
	v_mov_b32_e32 v25, v205
	v_or_b32_e32 v24, 0x1000, v2
	v_lshl_add_u64 v[26:27], v[20:21], 0, v[24:25]
	global_load_dwordx4 v[116:119], v226, s[98:99] offset:128
	global_load_dwordx4 v[112:115], v227, s[98:99]
	global_load_dwordx4 v[108:111], v227, s[98:99] offset:128
	global_load_dwordx4 v[104:107], v228, s[98:99]
	s_nop 0
	global_load_dwordx4 v[16:19], v229, s[100:101]
	v_mov_b32_e32 v29, v205
	v_or_b32_e32 v28, 0x2000, v2
	v_or_b32_e32 v2, 0x3000, v2
	global_load_dwordx4 v[100:103], v228, s[98:99] offset:128
	v_lshl_add_u64 v[30:31], v[20:21], 0, v[28:29]
	v_lshl_add_u64 v[20:21], v[20:21], 0, v[2:3]
	global_load_dwordx4 v[96:99], v229, s[98:99]
	global_load_dwordx4 v[92:95], v229, s[98:99] offset:128
	global_load_dwordx4 v[80:83], v226, s[98:99] offset:256
	global_load_dwordx4 v[76:79], v227, s[98:99] offset:256
	global_load_dwordx4 v[68:71], v228, s[98:99] offset:256
	global_load_dwordx4 v[64:67], v229, s[98:99] offset:256
	global_load_dwordx4 v[88:91], v226, s[98:99] offset:384
	global_load_dwordx4 v[84:87], v227, s[98:99] offset:384
	global_load_dwordx4 v[72:75], v228, s[98:99] offset:384
	v_and_or_b32 v126, v236, 32, s36
	ds_read_b128 v[148:151], v126 offset:8192
	ds_read_b128 v[144:147], v126 offset:8208
	ds_read_b128 v[128:131], v126 offset:8256
	ds_read_b128 v[132:135], v126 offset:8272
	ds_read_b128 v[136:139], v126 offset:8320
	ds_read_b128 v[140:143], v126 offset:8336
	ds_read_b128 v[156:159], v126 offset:8384
	ds_read_b128 v[152:155], v126 offset:8400
	v_lshl_add_u64 v[160:161], v[0:1], 0, v[2:3]
	s_mul_i32 s0, s4, 0x8100
	s_mul_hi_i32 s1, s4, 0x8100
	s_add_u32 s0, s88, s0
	s_addc_u32 s1, s89, s1
	v_lshl_add_u64 v[208:209], s[0:1], 0, v[204:205]
	v_lshlrev_b32_e32 v204, 8, v206
	v_lshl_add_u64 v[208:209], v[208:209], 0, v[204:205]
	v_lshlrev_b32_e32 v237, 4, v206
	v_lshl_or_b32 v237, v56, 9, v237
	v_mov_b32_e32 v238, s0
	v_mov_b32_e32 v239, s1
	v_add_co_u32_e32 v238, vcc, v238, v237
	s_nop 1
	v_addc_co_u32_e32 v239, vcc, 0, v239, vcc
	v_add_co_u32_e32 v240, vcc, 0x1000, v238
	s_nop 1
	v_addc_co_u32_e32 v241, vcc, 0, v239, vcc
	v_add_co_u32_e32 v242, vcc, 0x2000, v238
	s_nop 1
	v_addc_co_u32_e32 v243, vcc, 0, v239, vcc
	v_add_co_u32_e32 v244, vcc, 0x3000, v238
	s_nop 1
	v_addc_co_u32_e32 v245, vcc, 0, v239, vcc
	v_add_co_u32_e32 v246, vcc, 0x4000, v238
	s_nop 1
	v_addc_co_u32_e32 v247, vcc, 0, v239, vcc
	v_add_co_u32_e32 v248, vcc, 0x5000, v238
	s_nop 1
	v_addc_co_u32_e32 v249, vcc, 0, v239, vcc
	v_add_co_u32_e32 v250, vcc, 0x6000, v238
	s_nop 1
	v_addc_co_u32_e32 v251, vcc, 0, v239, vcc
	v_add_co_u32_e32 v252, vcc, 0x7000, v238
	s_nop 1
	v_addc_co_u32_e32 v253, vcc, 0, v239, vcc
	s_movk_i32 s0, 0x6000
	v_cmp_eq_u32_e64 s[4:5], 0, v206
	s_waitcnt vmcnt(18)
	v_lshlrev_b32_e32 v22, 16, v4
	v_and_b32_e32 v23, 0xffff0000, v4
	v_lshlrev_b32_e32 v4, 16, v5
	v_and_b32_e32 v5, 0xffff0000, v5
	s_waitcnt vmcnt(17)
	v_lshlrev_b32_e32 v30, 16, v8
	v_and_b32_e32 v31, 0xffff0000, v8
	v_lshlrev_b32_e32 v8, 16, v9
	v_and_b32_e32 v9, 0xffff0000, v9
	s_waitcnt lgkmcnt(7)
	v_pk_mul_f32 v[22:23], v[148:149], v[22:23]
	v_pk_mul_f32 v[32:33], v[150:151], v[4:5]
	v_cvt_pk_bf16_f32 v4, v22, v23
	s_waitcnt vmcnt(15)
	v_lshlrev_b32_e32 v22, 16, v12
	v_and_b32_e32 v23, 0xffff0000, v12
	s_waitcnt lgkmcnt(5)
	v_pk_mul_f32 v[8:9], v[130:131], v[8:9]
	v_lshlrev_b32_e32 v124, 16, v10
	v_cvt_pk_bf16_f32 v211, v8, v9
	s_waitcnt lgkmcnt(3)
	v_pk_mul_f32 v[8:9], v[136:137], v[22:23]
	v_and_b32_e32 v125, 0xffff0000, v10
	v_cvt_pk_bf16_f32 v214, v8, v9
	s_waitcnt vmcnt(10)
	v_lshlrev_b32_e32 v8, 16, v16
	v_and_b32_e32 v9, 0xffff0000, v16
	s_waitcnt lgkmcnt(1)
	v_pk_mul_f32 v[8:9], v[156:157], v[8:9]
	v_pk_mul_f32 v[124:125], v[132:133], v[124:125]
	v_cvt_pk_bf16_f32 v218, v8, v9
	v_lshl_add_u64 v[8:9], v[0:1], 0, v[24:25]
	v_cvt_pk_bf16_f32 v212, v124, v125
	global_load_dwordx4 v[124:127], v229, s[98:99] offset:384
	global_load_dwordx4 v[222:225], v226, s[100:101] offset:128
	global_load_dwordx4 v[200:203], v227, s[100:101] offset:128
	global_load_dwordx4 v[196:199], v228, s[100:101] offset:128
	global_load_dwordx4 v[192:195], v229, s[100:101] offset:128
	v_lshlrev_b32_e32 v26, 16, v6
	v_and_b32_e32 v27, 0xffff0000, v6
	v_lshlrev_b32_e32 v6, 16, v7
	v_and_b32_e32 v7, 0xffff0000, v7
	v_lshlrev_b32_e32 v10, 16, v11
	v_and_b32_e32 v11, 0xffff0000, v11
	v_pk_mul_f32 v[26:27], v[144:145], v[26:27]
	v_pk_mul_f32 v[34:35], v[146:147], v[6:7]
	v_cvt_pk_bf16_f32 v6, v26, v27
	v_lshlrev_b32_e32 v12, 16, v13
	v_and_b32_e32 v13, 0xffff0000, v13
	v_lshlrev_b32_e32 v26, 16, v14
	v_and_b32_e32 v27, 0xffff0000, v14
	v_pk_mul_f32 v[10:11], v[134:135], v[10:11]
	v_lshlrev_b32_e32 v14, 16, v15
	v_and_b32_e32 v15, 0xffff0000, v15
	v_lshl_add_u64 v[8:9], v[0:1], 0, v[28:29]
	v_cvt_pk_bf16_f32 v5, v32, v33
	v_cvt_pk_bf16_f32 v7, v34, v35
	v_pk_mul_f32 v[30:31], v[128:129], v[30:31]
	v_cvt_pk_bf16_f32 v213, v10, v11
	v_pk_mul_f32 v[10:11], v[138:139], v[12:13]
	v_pk_mul_f32 v[12:13], v[140:141], v[26:27]
	v_pk_mul_f32 v[14:15], v[142:143], v[14:15]
	global_load_dwordx4 v[188:191], v226, s[100:101] offset:256
	global_load_dwordx4 v[184:187], v227, s[100:101] offset:256
	global_load_dwordx4 v[180:183], v228, s[100:101] offset:256
	global_load_dwordx4 v[176:179], v229, s[100:101] offset:256
	v_cvt_pk_bf16_f32 v210, v30, v31
	v_cvt_pk_bf16_f32 v215, v10, v11
	v_cvt_pk_bf16_f32 v216, v12, v13
	v_cvt_pk_bf16_f32 v217, v14, v15
	v_lshlrev_b32_e32 v10, 16, v17
	v_and_b32_e32 v11, 0xffff0000, v17
	v_lshlrev_b32_e32 v12, 16, v18
	v_and_b32_e32 v13, 0xffff0000, v18
	v_lshlrev_b32_e32 v14, 16, v19
	v_and_b32_e32 v15, 0xffff0000, v19
	s_waitcnt vmcnt(15)
	v_mfma_f32_32x32x16_bf16 v[16:31], v[80:83], v[4:7], 0
	v_mul_f32_e64 v10, v158, v10
	v_mul_f32_e64 v11, v159, v11
	s_waitcnt lgkmcnt(0)
	v_mul_f32_e64 v12, v152, v12
	v_mul_f32_e64 v13, v153, v13
	v_pk_mul_f32 v[14:15], v[154:155], v[14:15]
	v_cvt_pk_bf16_f32 v219, v10, v11
	v_cvt_pk_bf16_f32 v220, v12, v13
	v_cvt_pk_bf16_f32 v221, v14, v15
	global_load_dwordx4 v[172:175], v226, s[100:101] offset:384
	global_load_dwordx4 v[168:171], v227, s[100:101] offset:384
	s_waitcnt vmcnt(16)
	v_mfma_f32_32x32x16_bf16 v[16:31], v[76:79], v[210:213], v[16:31]
	global_load_dwordx4 v[164:167], v228, s[100:101] offset:384
	s_nop 0
	global_load_dwordx4 v[160:163], v229, s[100:101] offset:384
	v_mfma_f32_32x32x16_bf16 v[32:47], v[116:119], v[4:7], 0
	s_waitcnt vmcnt(17)
	v_mfma_f32_32x32x16_bf16 v[16:31], v[68:71], v[214:217], v[16:31]
	v_mfma_f32_32x32x16_bf16 v[48:63], v[120:123], v[4:7], 0
	v_mfma_f32_32x32x16_bf16 v[32:47], v[108:111], v[210:213], v[32:47]
	s_waitcnt vmcnt(15)
	v_mfma_f32_32x32x16_bf16 v[0:15], v[88:91], v[4:7], 0
	v_mfma_f32_32x32x16_bf16 v[16:31], v[64:67], v[218:221], v[16:31]
	v_mfma_f32_32x32x16_bf16 v[48:63], v[112:115], v[210:213], v[48:63]
	s_nop 10
	v_cvt_pk_bf16_f32 v16, v16, v17
	v_cvt_pk_bf16_f32 v17, v18, v19
	v_cvt_pk_bf16_f32 v18, v20, v21
	v_cvt_pk_bf16_f32 v19, v22, v23
	s_nop 0
	v_permlane32_swap_b32_e32 v16, v18
	v_permlane32_swap_b32_e32 v17, v19
	v_mfma_f32_32x32x16_bf16 v[32:47], v[100:103], v[214:217], v[32:47]
	global_store_dwordx4 v[240:241], v[16:19], off
	s_waitcnt vmcnt(12)
	v_lshlrev_b32_e32 v20, 16, v222
	v_and_b32_e32 v21, 0xffff0000, v222
	v_cvt_pk_bf16_f32 v16, v24, v25
	v_cvt_pk_bf16_f32 v17, v26, v27
	v_lshlrev_b32_e32 v22, 16, v223
	v_and_b32_e32 v23, 0xffff0000, v223
	v_mfma_f32_32x32x16_bf16 v[0:15], v[84:87], v[210:213], v[0:15]
	v_lshlrev_b32_e32 v24, 16, v224
	v_and_b32_e32 v25, 0xffff0000, v224
	v_lshlrev_b32_e32 v26, 16, v225
	v_and_b32_e32 v27, 0xffff0000, v225
	v_mul_f32_e64 v20, v148, v20
	v_mul_f32_e64 v21, v149, v21
	v_pk_mul_f32 v[22:23], v[150:151], v[22:23]
	v_pk_mul_f32 v[24:25], v[144:145], v[24:25]
	v_mfma_f32_32x32x16_bf16 v[48:63], v[104:107], v[214:217], v[48:63]
	v_mul_f32_e64 v26, v146, v26
	v_mul_f32_e64 v27, v147, v27
	v_cvt_pk_bf16_f32 v210, v20, v21
	v_cvt_pk_bf16_f32 v211, v22, v23
	v_cvt_pk_bf16_f32 v212, v24, v25
	v_cvt_pk_bf16_f32 v213, v26, v27
	s_waitcnt vmcnt(11)
	v_lshlrev_b32_e32 v20, 16, v200
	v_and_b32_e32 v21, 0xffff0000, v200
	v_lshlrev_b32_e32 v22, 16, v201
	v_and_b32_e32 v23, 0xffff0000, v201
	v_lshlrev_b32_e32 v24, 16, v202
	v_and_b32_e32 v25, 0xffff0000, v202
	v_lshlrev_b32_e32 v26, 16, v203
	v_and_b32_e32 v27, 0xffff0000, v203
	v_pk_mul_f32 v[20:21], v[128:129], v[20:21]
	v_pk_mul_f32 v[22:23], v[130:131], v[22:23]
	v_pk_mul_f32 v[24:25], v[132:133], v[24:25]
	v_pk_mul_f32 v[26:27], v[134:135], v[26:27]
	v_cvt_pk_bf16_f32 v200, v20, v21
	v_cvt_pk_bf16_f32 v201, v22, v23
	v_cvt_pk_bf16_f32 v202, v24, v25
	v_cvt_pk_bf16_f32 v203, v26, v27
	s_waitcnt vmcnt(10)
	v_lshlrev_b32_e32 v20, 16, v196
	v_and_b32_e32 v21, 0xffff0000, v196
	v_lshlrev_b32_e32 v22, 16, v197
	v_and_b32_e32 v23, 0xffff0000, v197
	v_lshlrev_b32_e32 v24, 16, v198
	v_and_b32_e32 v25, 0xffff0000, v198
	v_lshlrev_b32_e32 v26, 16, v199
	v_and_b32_e32 v27, 0xffff0000, v199
	v_pk_mul_f32 v[20:21], v[136:137], v[20:21]
	v_pk_mul_f32 v[22:23], v[138:139], v[22:23]
	v_pk_mul_f32 v[24:25], v[140:141], v[24:25]
	v_pk_mul_f32 v[26:27], v[142:143], v[26:27]
	v_mfma_f32_32x32x16_bf16 v[32:47], v[92:95], v[218:221], v[32:47]
	v_cvt_pk_bf16_f32 v18, v28, v29
	v_cvt_pk_bf16_f32 v196, v20, v21
	v_cvt_pk_bf16_f32 v197, v22, v23
	v_cvt_pk_bf16_f32 v198, v24, v25
	v_cvt_pk_bf16_f32 v199, v26, v27
	s_waitcnt vmcnt(9)
	v_lshlrev_b32_e32 v20, 16, v192
	v_and_b32_e32 v21, 0xffff0000, v192
	v_mfma_f32_32x32x16_bf16 v[0:15], v[72:75], v[214:217], v[0:15]
	v_lshlrev_b32_e32 v22, 16, v193
	v_and_b32_e32 v23, 0xffff0000, v193
	v_lshlrev_b32_e32 v24, 16, v194
	v_and_b32_e32 v25, 0xffff0000, v194
	v_lshlrev_b32_e32 v26, 16, v195
	v_and_b32_e32 v27, 0xffff0000, v195
	v_cvt_pk_bf16_f32 v19, v30, v31
	v_pk_mul_f32 v[20:21], v[156:157], v[20:21]
	v_pk_mul_f32 v[22:23], v[158:159], v[22:23]
	v_pk_mul_f32 v[24:25], v[152:153], v[24:25]
	v_pk_mul_f32 v[26:27], v[154:155], v[26:27]
	v_permlane32_swap_b32_e32 v16, v18
	v_permlane32_swap_b32_e32 v17, v19
	v_mfma_f32_32x32x16_bf16 v[48:63], v[96:99], v[218:221], v[48:63]
	v_cvt_pk_bf16_f32 v214, v20, v21
	v_cvt_pk_bf16_f32 v215, v22, v23
	v_cvt_pk_bf16_f32 v216, v24, v25
	v_cvt_pk_bf16_f32 v217, v26, v27
	global_store_dwordx4 v[240:241], v[16:19], off offset:1024
	v_cvt_pk_bf16_f32 v32, v32, v33
	v_cvt_pk_bf16_f32 v33, v34, v35
	v_mfma_f32_32x32x16_bf16 v[16:31], v[80:83], v[210:213], 0
	v_cvt_pk_bf16_f32 v34, v36, v37
	v_cvt_pk_bf16_f32 v35, v38, v39
	s_nop 0
	v_permlane32_swap_b32_e32 v32, v34
	v_permlane32_swap_b32_e32 v33, v35
	v_cvt_pk_bf16_f32 v48, v48, v49
	v_mfma_f32_32x32x16_bf16 v[0:15], v[124:127], v[218:221], v[0:15]
	v_cvt_pk_bf16_f32 v49, v50, v51
	v_cvt_pk_bf16_f32 v50, v52, v53
	v_cvt_pk_bf16_f32 v51, v54, v55
	global_store_dwordx4 v[238:239], v[32:35], off offset:2048
	v_permlane32_swap_b32_e32 v48, v50
	s_nop 0
	v_cvt_pk_bf16_f32 v32, v40, v41
	v_cvt_pk_bf16_f32 v33, v42, v43
	v_cvt_pk_bf16_f32 v34, v44, v45
	v_cvt_pk_bf16_f32 v35, v46, v47
	v_mfma_f32_32x32x16_bf16 v[16:31], v[76:79], v[200:203], v[16:31]
	v_permlane32_swap_b32_e32 v49, v51
	v_permlane32_swap_b32_e32 v32, v34
	v_permlane32_swap_b32_e32 v33, v35
	global_store_dwordx4 v[238:239], v[48:51], off
	global_store_dwordx4 v[238:239], v[32:35], off offset:3072
	v_cvt_pk_bf16_f32 v0, v0, v1
	v_cvt_pk_bf16_f32 v48, v56, v57
	v_cvt_pk_bf16_f32 v49, v58, v59
	v_cvt_pk_bf16_f32 v50, v60, v61
	v_cvt_pk_bf16_f32 v51, v62, v63
	v_mfma_f32_32x32x16_bf16 v[32:47], v[116:119], v[210:213], 0
	v_permlane32_swap_b32_e32 v48, v50
	v_permlane32_swap_b32_e32 v49, v51
	global_store_dwordx4 v[238:239], v[48:51], off offset:1024
	v_cvt_pk_bf16_f32 v1, v2, v3
	v_cvt_pk_bf16_f32 v2, v4, v5
	v_mfma_f32_32x32x16_bf16 v[48:63], v[120:123], v[210:213], 0
	v_cvt_pk_bf16_f32 v3, v6, v7
	v_permlane32_swap_b32_e32 v0, v2
	s_nop 0
	v_permlane32_swap_b32_e32 v1, v3
	global_store_dwordx4 v[240:241], v[0:3], off offset:2048
	v_cvt_pk_bf16_f32 v192, v8, v9
	v_cvt_pk_bf16_f32 v193, v10, v11
	v_cvt_pk_bf16_f32 v194, v12, v13
	v_cvt_pk_bf16_f32 v195, v14, v15
	v_mfma_f32_32x32x16_bf16 v[0:15], v[88:91], v[210:213], 0
	v_permlane32_swap_b32_e32 v192, v194
	v_permlane32_swap_b32_e32 v193, v195
	global_store_dwordx4 v[240:241], v[192:195], off offset:3072
	v_mfma_f32_32x32x16_bf16 v[16:31], v[68:71], v[196:199], v[16:31]
	s_nop 0
	v_add_co_u32_e32 v192, vcc, s94, v208
	s_nop 1
	v_addc_co_u32_e32 v193, vcc, 0, v209, vcc
	v_mfma_f32_32x32x16_bf16 v[32:47], v[108:111], v[200:203], v[32:47]
	v_mfma_f32_32x32x16_bf16 v[48:63], v[112:115], v[200:203], v[48:63]
	v_mfma_f32_32x32x16_bf16 v[0:15], v[84:87], v[200:203], v[0:15]
	v_mfma_f32_32x32x16_bf16 v[16:31], v[64:67], v[214:217], v[16:31]
	v_mfma_f32_32x32x16_bf16 v[32:47], v[100:103], v[196:199], v[32:47]
	s_nop 10
	v_cvt_pk_bf16_f32 v16, v16, v17
	v_cvt_pk_bf16_f32 v17, v18, v19
	v_cvt_pk_bf16_f32 v18, v20, v21
	v_cvt_pk_bf16_f32 v19, v22, v23
	s_nop 0
	v_permlane32_swap_b32_e32 v16, v18
	v_permlane32_swap_b32_e32 v17, v19
	v_mfma_f32_32x32x16_bf16 v[48:63], v[104:107], v[196:199], v[48:63]
	global_store_dwordx4 v[244:245], v[16:19], off
	s_waitcnt vmcnt(16)
	v_lshlrev_b32_e32 v20, 16, v188
	v_and_b32_e32 v21, 0xffff0000, v188
	v_cvt_pk_bf16_f32 v16, v24, v25
	v_cvt_pk_bf16_f32 v17, v26, v27
	v_lshlrev_b32_e32 v22, 16, v189
	v_and_b32_e32 v23, 0xffff0000, v189
	v_mfma_f32_32x32x16_bf16 v[0:15], v[72:75], v[196:199], v[0:15]
	v_lshlrev_b32_e32 v24, 16, v190
	v_and_b32_e32 v25, 0xffff0000, v190
	v_lshlrev_b32_e32 v26, 16, v191
	v_and_b32_e32 v27, 0xffff0000, v191
	v_mul_f32_e64 v20, v148, v20
	v_mul_f32_e64 v21, v149, v21
	v_pk_mul_f32 v[22:23], v[150:151], v[22:23]
	v_pk_mul_f32 v[24:25], v[144:145], v[24:25]
	v_mfma_f32_32x32x16_bf16 v[32:47], v[92:95], v[214:217], v[32:47]
	v_mul_f32_e64 v26, v146, v26
	v_mul_f32_e64 v27, v147, v27
	v_cvt_pk_bf16_f32 v188, v20, v21
	v_cvt_pk_bf16_f32 v189, v22, v23
	v_cvt_pk_bf16_f32 v190, v24, v25
	v_cvt_pk_bf16_f32 v191, v26, v27
	s_waitcnt vmcnt(15)
	v_lshlrev_b32_e32 v20, 16, v184
	v_and_b32_e32 v21, 0xffff0000, v184
	v_mfma_f32_32x32x16_bf16 v[48:63], v[96:99], v[214:217], v[48:63]
	v_lshlrev_b32_e32 v22, 16, v185
	v_and_b32_e32 v23, 0xffff0000, v185
	v_lshlrev_b32_e32 v24, 16, v186
	v_and_b32_e32 v25, 0xffff0000, v186
	v_lshlrev_b32_e32 v26, 16, v187
	v_and_b32_e32 v27, 0xffff0000, v187
	v_pk_mul_f32 v[20:21], v[128:129], v[20:21]
	v_pk_mul_f32 v[22:23], v[130:131], v[22:23]
	v_pk_mul_f32 v[24:25], v[132:133], v[24:25]
	v_pk_mul_f32 v[26:27], v[134:135], v[26:27]
	v_cvt_pk_bf16_f32 v184, v20, v21
	v_cvt_pk_bf16_f32 v185, v22, v23
	v_cvt_pk_bf16_f32 v186, v24, v25
	v_cvt_pk_bf16_f32 v187, v26, v27
	s_waitcnt vmcnt(14)
	v_lshlrev_b32_e32 v20, 16, v180
	v_and_b32_e32 v21, 0xffff0000, v180
	v_lshlrev_b32_e32 v22, 16, v181
	v_and_b32_e32 v23, 0xffff0000, v181
	v_lshlrev_b32_e32 v24, 16, v182
	v_and_b32_e32 v25, 0xffff0000, v182
	v_lshlrev_b32_e32 v26, 16, v183
	v_and_b32_e32 v27, 0xffff0000, v183
	v_pk_mul_f32 v[20:21], v[136:137], v[20:21]
	v_pk_mul_f32 v[22:23], v[138:139], v[22:23]
	v_pk_mul_f32 v[24:25], v[140:141], v[24:25]
	v_pk_mul_f32 v[26:27], v[142:143], v[26:27]
	v_mfma_f32_32x32x16_bf16 v[0:15], v[124:127], v[214:217], v[0:15]
	v_cvt_pk_bf16_f32 v18, v28, v29
	v_cvt_pk_bf16_f32 v180, v20, v21
	v_cvt_pk_bf16_f32 v181, v22, v23
	v_cvt_pk_bf16_f32 v182, v24, v25
	v_cvt_pk_bf16_f32 v183, v26, v27
	s_waitcnt vmcnt(13)
	v_lshlrev_b32_e32 v20, 16, v176
	v_and_b32_e32 v21, 0xffff0000, v176
	v_lshlrev_b32_e32 v22, 16, v177
	v_and_b32_e32 v23, 0xffff0000, v177
	v_lshlrev_b32_e32 v24, 16, v178
	v_and_b32_e32 v25, 0xffff0000, v178
	v_lshlrev_b32_e32 v26, 16, v179
	v_and_b32_e32 v27, 0xffff0000, v179
	v_cvt_pk_bf16_f32 v19, v30, v31
	v_pk_mul_f32 v[20:21], v[156:157], v[20:21]
	v_pk_mul_f32 v[22:23], v[158:159], v[22:23]
	v_pk_mul_f32 v[24:25], v[152:153], v[24:25]
	v_pk_mul_f32 v[26:27], v[154:155], v[26:27]
	v_permlane32_swap_b32_e32 v16, v18
	v_permlane32_swap_b32_e32 v17, v19
	v_cvt_pk_bf16_f32 v32, v32, v33
	v_cvt_pk_bf16_f32 v33, v34, v35
	v_cvt_pk_bf16_f32 v34, v36, v37
	v_cvt_pk_bf16_f32 v35, v38, v39
	v_cvt_pk_bf16_f32 v194, v20, v21
	v_cvt_pk_bf16_f32 v195, v22, v23
	v_cvt_pk_bf16_f32 v196, v24, v25
	v_cvt_pk_bf16_f32 v197, v26, v27
	global_store_dwordx4 v[244:245], v[16:19], off offset:1024
	v_permlane32_swap_b32_e32 v32, v34
	s_nop 0
	v_mfma_f32_32x32x16_bf16 v[16:31], v[80:83], v[188:191], 0
	v_permlane32_swap_b32_e32 v33, v35
	v_cvt_pk_bf16_f32 v48, v48, v49
	v_cvt_pk_bf16_f32 v49, v50, v51
	v_cvt_pk_bf16_f32 v50, v52, v53
	v_cvt_pk_bf16_f32 v51, v54, v55
	global_store_dwordx4 v[242:243], v[32:35], off offset:2048
	v_permlane32_swap_b32_e32 v48, v50
	s_nop 0
	v_cvt_pk_bf16_f32 v32, v40, v41
	v_cvt_pk_bf16_f32 v33, v42, v43
	v_cvt_pk_bf16_f32 v34, v44, v45
	v_cvt_pk_bf16_f32 v35, v46, v47
	v_permlane32_swap_b32_e32 v49, v51
	v_permlane32_swap_b32_e32 v32, v34
	v_permlane32_swap_b32_e32 v33, v35
	global_store_dwordx4 v[242:243], v[48:51], off
	global_store_dwordx4 v[242:243], v[32:35], off offset:3072
	v_cvt_pk_bf16_f32 v0, v0, v1
	v_cvt_pk_bf16_f32 v48, v56, v57
	v_cvt_pk_bf16_f32 v49, v58, v59
	v_cvt_pk_bf16_f32 v50, v60, v61
	v_cvt_pk_bf16_f32 v51, v62, v63
	v_mfma_f32_32x32x16_bf16 v[32:47], v[116:119], v[188:191], 0
	v_permlane32_swap_b32_e32 v48, v50
	v_permlane32_swap_b32_e32 v49, v51
	global_store_dwordx4 v[242:243], v[48:51], off offset:1024
	v_cvt_pk_bf16_f32 v1, v2, v3
	v_cvt_pk_bf16_f32 v2, v4, v5
	v_mfma_f32_32x32x16_bf16 v[48:63], v[120:123], v[188:191], 0
	v_cvt_pk_bf16_f32 v3, v6, v7
	v_permlane32_swap_b32_e32 v0, v2
	s_nop 0
	v_permlane32_swap_b32_e32 v1, v3
	global_store_dwordx4 v[244:245], v[0:3], off offset:2048
	v_cvt_pk_bf16_f32 v176, v8, v9
	v_cvt_pk_bf16_f32 v177, v10, v11
	v_cvt_pk_bf16_f32 v178, v12, v13
	v_cvt_pk_bf16_f32 v179, v14, v15
	v_mfma_f32_32x32x16_bf16 v[0:15], v[88:91], v[188:191], 0
	v_permlane32_swap_b32_e32 v176, v178
	v_permlane32_swap_b32_e32 v177, v179
	global_store_dwordx4 v[244:245], v[176:179], off offset:3072
	v_mfma_f32_32x32x16_bf16 v[16:31], v[76:79], v[184:187], v[16:31]
	s_nop 0
	v_add_co_u32_e32 v176, vcc, s95, v208
	s_nop 1
	v_addc_co_u32_e32 v177, vcc, 0, v209, vcc
	v_mfma_f32_32x32x16_bf16 v[32:47], v[108:111], v[184:187], v[32:47]
	v_mfma_f32_32x32x16_bf16 v[48:63], v[112:115], v[184:187], v[48:63]
	v_mfma_f32_32x32x16_bf16 v[0:15], v[84:87], v[184:187], v[0:15]
	v_mfma_f32_32x32x16_bf16 v[16:31], v[68:71], v[180:183], v[16:31]
	v_mfma_f32_32x32x16_bf16 v[32:47], v[100:103], v[180:183], v[32:47]
	v_mfma_f32_32x32x16_bf16 v[48:63], v[104:107], v[180:183], v[48:63]
	v_mfma_f32_32x32x16_bf16 v[0:15], v[72:75], v[180:183], v[0:15]
	v_mfma_f32_32x32x16_bf16 v[16:31], v[64:67], v[194:197], v[16:31]
	v_mfma_f32_32x32x16_bf16 v[32:47], v[92:95], v[194:197], v[32:47]
	s_nop 10
	v_cvt_pk_bf16_f32 v16, v16, v17
	v_cvt_pk_bf16_f32 v17, v18, v19
	v_cvt_pk_bf16_f32 v18, v20, v21
	v_cvt_pk_bf16_f32 v19, v22, v23
	s_nop 0
	v_permlane32_swap_b32_e32 v16, v18
	v_permlane32_swap_b32_e32 v17, v19
	v_mfma_f32_32x32x16_bf16 v[48:63], v[96:99], v[194:197], v[48:63]
	global_store_dwordx4 v[248:249], v[16:19], off
	s_waitcnt vmcnt(20)
	v_lshlrev_b32_e32 v20, 16, v172
	v_and_b32_e32 v21, 0xffff0000, v172
	v_cvt_pk_bf16_f32 v16, v24, v25
	v_cvt_pk_bf16_f32 v17, v26, v27
	v_lshlrev_b32_e32 v22, 16, v173
	v_and_b32_e32 v23, 0xffff0000, v173
	v_mfma_f32_32x32x16_bf16 v[0:15], v[124:127], v[194:197], v[0:15]
	v_lshlrev_b32_e32 v24, 16, v174
	v_and_b32_e32 v25, 0xffff0000, v174
	v_lshlrev_b32_e32 v26, 16, v175
	v_and_b32_e32 v27, 0xffff0000, v175
	v_mul_f32_e64 v20, v148, v20
	v_mul_f32_e64 v21, v149, v21
	v_pk_mul_f32 v[22:23], v[150:151], v[22:23]
	v_pk_mul_f32 v[24:25], v[144:145], v[24:25]
	v_pk_mul_f32 v[26:27], v[146:147], v[26:27]
	v_cvt_pk_bf16_f32 v32, v32, v33
	v_cvt_pk_bf16_f32 v33, v34, v35
	v_cvt_pk_bf16_f32 v34, v36, v37
	v_cvt_pk_bf16_f32 v35, v38, v39
	v_cvt_pk_bf16_f32 v172, v20, v21
	v_cvt_pk_bf16_f32 v173, v22, v23
	v_cvt_pk_bf16_f32 v174, v24, v25
	v_cvt_pk_bf16_f32 v175, v26, v27
	s_waitcnt vmcnt(19)
	v_lshlrev_b32_e32 v20, 16, v168
	v_and_b32_e32 v21, 0xffff0000, v168
	v_lshlrev_b32_e32 v22, 16, v169
	v_and_b32_e32 v23, 0xffff0000, v169
	v_lshlrev_b32_e32 v24, 16, v170
	v_and_b32_e32 v25, 0xffff0000, v170
	v_lshlrev_b32_e32 v26, 16, v171
	v_and_b32_e32 v27, 0xffff0000, v171
	v_permlane32_swap_b32_e32 v32, v34
	v_permlane32_swap_b32_e32 v33, v35
	v_pk_mul_f32 v[20:21], v[128:129], v[20:21]
	v_pk_mul_f32 v[22:23], v[130:131], v[22:23]
	v_pk_mul_f32 v[24:25], v[132:133], v[24:25]
	v_pk_mul_f32 v[26:27], v[134:135], v[26:27]
	v_cvt_pk_bf16_f32 v48, v48, v49
	v_cvt_pk_bf16_f32 v49, v50, v51
	v_cvt_pk_bf16_f32 v50, v52, v53
	v_cvt_pk_bf16_f32 v51, v54, v55
	global_store_dwordx4 v[246:247], v[32:35], off offset:2048
	v_cvt_pk_bf16_f32 v168, v20, v21
	v_cvt_pk_bf16_f32 v169, v22, v23
	v_cvt_pk_bf16_f32 v32, v40, v41
	v_cvt_pk_bf16_f32 v33, v42, v43
	v_cvt_pk_bf16_f32 v34, v44, v45
	v_cvt_pk_bf16_f32 v35, v46, v47
	v_cvt_pk_bf16_f32 v170, v24, v25
	v_cvt_pk_bf16_f32 v171, v26, v27
	s_waitcnt vmcnt(19)
	v_lshlrev_b32_e32 v20, 16, v164
	v_and_b32_e32 v21, 0xffff0000, v164
	v_lshlrev_b32_e32 v22, 16, v165
	v_and_b32_e32 v23, 0xffff0000, v165
	v_lshlrev_b32_e32 v24, 16, v166
	v_and_b32_e32 v25, 0xffff0000, v166
	v_lshlrev_b32_e32 v26, 16, v167
	v_and_b32_e32 v27, 0xffff0000, v167
	v_permlane32_swap_b32_e32 v48, v50
	v_permlane32_swap_b32_e32 v49, v51
	v_permlane32_swap_b32_e32 v32, v34
	v_permlane32_swap_b32_e32 v33, v35
	v_pk_mul_f32 v[20:21], v[136:137], v[20:21]
	v_pk_mul_f32 v[22:23], v[138:139], v[22:23]
	v_pk_mul_f32 v[24:25], v[140:141], v[24:25]
	v_pk_mul_f32 v[26:27], v[142:143], v[26:27]
	global_store_dwordx4 v[246:247], v[48:51], off
	global_store_dwordx4 v[246:247], v[32:35], off offset:3072
	v_cvt_pk_bf16_f32 v18, v28, v29
	v_cvt_pk_bf16_f32 v48, v56, v57
	v_cvt_pk_bf16_f32 v49, v58, v59
	v_cvt_pk_bf16_f32 v50, v60, v61
	v_cvt_pk_bf16_f32 v51, v62, v63
	v_mfma_f32_32x32x16_bf16 v[32:47], v[116:119], v[172:175], 0
	v_cvt_pk_bf16_f32 v164, v20, v21
	v_cvt_pk_bf16_f32 v165, v22, v23
	v_cvt_pk_bf16_f32 v166, v24, v25
	v_cvt_pk_bf16_f32 v167, v26, v27
	s_waitcnt vmcnt(20)
	v_lshlrev_b32_e32 v20, 16, v160
	v_and_b32_e32 v21, 0xffff0000, v160
	v_lshlrev_b32_e32 v22, 16, v161
	v_and_b32_e32 v23, 0xffff0000, v161
	v_lshlrev_b32_e32 v24, 16, v162
	v_and_b32_e32 v25, 0xffff0000, v162
	v_lshlrev_b32_e32 v26, 16, v163
	v_and_b32_e32 v27, 0xffff0000, v163
	v_cvt_pk_bf16_f32 v19, v30, v31
	v_cvt_pk_bf16_f32 v0, v0, v1
	v_cvt_pk_bf16_f32 v1, v2, v3
	v_cvt_pk_bf16_f32 v2, v4, v5
	v_cvt_pk_bf16_f32 v3, v6, v7
	v_permlane32_swap_b32_e32 v48, v50
	v_permlane32_swap_b32_e32 v49, v51
	v_pk_mul_f32 v[20:21], v[156:157], v[20:21]
	v_pk_mul_f32 v[22:23], v[158:159], v[22:23]
	v_pk_mul_f32 v[24:25], v[152:153], v[24:25]
	v_pk_mul_f32 v[26:27], v[154:155], v[26:27]
	v_permlane32_swap_b32_e32 v16, v18
	v_permlane32_swap_b32_e32 v17, v19
	v_permlane32_swap_b32_e32 v0, v2
	v_permlane32_swap_b32_e32 v1, v3
	global_store_dwordx4 v[246:247], v[48:51], off offset:1024
	v_cvt_pk_bf16_f32 v160, v20, v21
	v_cvt_pk_bf16_f32 v161, v22, v23
	v_mfma_f32_32x32x16_bf16 v[48:63], v[120:123], v[172:175], 0
	v_cvt_pk_bf16_f32 v162, v24, v25
	v_cvt_pk_bf16_f32 v163, v26, v27
	global_store_dwordx4 v[248:249], v[16:19], off offset:1024
	global_store_dwordx4 v[248:249], v[0:3], off offset:2048
	v_cvt_pk_bf16_f32 v178, v8, v9
	v_cvt_pk_bf16_f32 v179, v10, v11
	v_cvt_pk_bf16_f32 v180, v12, v13
	v_mfma_f32_32x32x16_bf16 v[16:31], v[80:83], v[172:175], 0
	v_cvt_pk_bf16_f32 v181, v14, v15
	v_permlane32_swap_b32_e32 v178, v180
	s_nop 0
	v_permlane32_swap_b32_e32 v179, v181
	global_store_dwordx4 v[248:249], v[178:181], off offset:3072
	v_mfma_f32_32x32x16_bf16 v[0:15], v[88:91], v[172:175], 0
	v_add_co_u32_e32 v172, vcc, s0, v208
	s_nop 1
	v_addc_co_u32_e32 v173, vcc, 0, v209, vcc
	v_mfma_f32_32x32x16_bf16 v[32:47], v[108:111], v[168:171], v[32:47]
	v_mfma_f32_32x32x16_bf16 v[48:63], v[112:115], v[168:171], v[48:63]
	v_mfma_f32_32x32x16_bf16 v[16:31], v[76:79], v[168:171], v[16:31]
	v_mfma_f32_32x32x16_bf16 v[0:15], v[84:87], v[168:171], v[0:15]
	v_mfma_f32_32x32x16_bf16 v[32:47], v[100:103], v[164:167], v[32:47]
	v_mfma_f32_32x32x16_bf16 v[48:63], v[104:107], v[164:167], v[48:63]
	v_mfma_f32_32x32x16_bf16 v[16:31], v[68:71], v[164:167], v[16:31]
	v_mfma_f32_32x32x16_bf16 v[0:15], v[72:75], v[164:167], v[0:15]
	v_mfma_f32_32x32x16_bf16 v[32:47], v[92:95], v[160:163], v[32:47]
	v_mfma_f32_32x32x16_bf16 v[48:63], v[96:99], v[160:163], v[48:63]
	s_nop 10
	v_cvt_pk_bf16_f32 v32, v32, v33
	v_cvt_pk_bf16_f32 v33, v34, v35
	v_cvt_pk_bf16_f32 v34, v36, v37
	v_cvt_pk_bf16_f32 v35, v38, v39
	s_nop 0
	v_permlane32_swap_b32_e32 v32, v34
	v_permlane32_swap_b32_e32 v33, v35
	v_mfma_f32_32x32x16_bf16 v[16:31], v[64:67], v[160:163], v[16:31]
	v_cvt_pk_bf16_f32 v48, v48, v49
	v_cvt_pk_bf16_f32 v49, v50, v51
	v_cvt_pk_bf16_f32 v50, v52, v53
	v_cvt_pk_bf16_f32 v51, v54, v55
	global_store_dwordx4 v[250:251], v[32:35], off offset:2048
	v_permlane32_swap_b32_e32 v48, v50
	v_mfma_f32_32x32x16_bf16 v[0:15], v[124:127], v[160:163], v[0:15]
	v_cvt_pk_bf16_f32 v32, v40, v41
	v_cvt_pk_bf16_f32 v33, v42, v43
	v_cvt_pk_bf16_f32 v34, v44, v45
	v_cvt_pk_bf16_f32 v35, v46, v47
	s_nop 0
	v_cvt_pk_bf16_f32 v16, v16, v17
	v_cvt_pk_bf16_f32 v17, v18, v19
	v_cvt_pk_bf16_f32 v18, v20, v21
	v_cvt_pk_bf16_f32 v19, v22, v23
	s_nop 2
	v_cvt_pk_bf16_f32 v52, v0, v1
	v_cvt_pk_bf16_f32 v53, v2, v3
	v_cvt_pk_bf16_f32 v54, v4, v5
	v_cvt_pk_bf16_f32 v55, v6, v7
	v_cndmask_b32_e64 v0, 0, v148, s[4:5]
	v_cndmask_b32_e64 v1, 0, v149, s[4:5]
	v_cndmask_b32_e64 v2, 0, v150, s[4:5]
	v_cndmask_b32_e64 v3, 0, v151, s[4:5]
	v_cndmask_b32_e64 v4, 0, v144, s[4:5]
	v_cndmask_b32_e64 v5, 0, v145, s[4:5]
	v_cndmask_b32_e64 v6, 0, v146, s[4:5]
	v_cndmask_b32_e64 v7, 0, v147, s[4:5]
	v_permlane32_swap_b32_e32 v32, v34
	v_permlane32_swap_b32_e32 v33, v35
	v_permlane32_swap_b32_e32 v16, v18
	v_permlane32_swap_b32_e32 v17, v19
	v_cvt_pk_bf16_f32 v0, v0, v1
	v_cvt_pk_bf16_f32 v1, v2, v3
	v_cvt_pk_bf16_f32 v2, v4, v5
	v_cvt_pk_bf16_f32 v3, v6, v7
	global_store_dwordx4 v[250:251], v[32:35], off offset:3072
	global_store_dwordx4 v[252:253], v[16:19], off
	v_permlane32_swap_b32_e32 v49, v51
	s_nop 0
	v_cvt_pk_bf16_f32 v16, v24, v25
	v_cvt_pk_bf16_f32 v17, v26, v27
	v_cvt_pk_bf16_f32 v18, v28, v29
	v_cvt_pk_bf16_f32 v19, v30, v31
	v_mfma_f32_32x32x16_bf16 v[32:47], v[120:123], v[0:3], 0
	v_permlane32_swap_b32_e32 v16, v18
	v_permlane32_swap_b32_e32 v17, v19
	global_store_dwordx4 v[252:253], v[16:19], off offset:1024
	global_store_dwordx4 v[250:251], v[48:51], off
	v_cndmask_b32_e64 v4, 0, v128, s[4:5]
	v_mfma_f32_32x32x16_bf16 v[16:31], v[116:119], v[0:3], 0
	v_cvt_pk_bf16_f32 v48, v56, v57
	v_cvt_pk_bf16_f32 v49, v58, v59
	v_cvt_pk_bf16_f32 v50, v60, v61
	v_cvt_pk_bf16_f32 v51, v62, v63
	s_nop 0
	v_permlane32_swap_b32_e32 v48, v50
	v_permlane32_swap_b32_e32 v49, v51
	global_store_dwordx4 v[250:251], v[48:51], off offset:1024
	v_cndmask_b32_e64 v5, 0, v129, s[4:5]
	v_cndmask_b32_e64 v6, 0, v130, s[4:5]
	v_cndmask_b32_e64 v7, 0, v131, s[4:5]
	v_cndmask_b32_e64 v50, 0, v132, s[4:5]
	v_cndmask_b32_e64 v51, 0, v133, s[4:5]
	v_cndmask_b32_e64 v56, 0, v134, s[4:5]
	v_cndmask_b32_e64 v57, 0, v135, s[4:5]
	v_cvt_pk_bf16_f32 v48, v4, v5
	v_cvt_pk_bf16_f32 v49, v6, v7
	v_cvt_pk_bf16_f32 v50, v50, v51
	v_cvt_pk_bf16_f32 v51, v56, v57
	v_permlane32_swap_b32_e32 v52, v54
	s_nop 0
	v_mfma_f32_32x32x16_bf16 v[32:47], v[112:115], v[48:51], v[32:47]
	v_permlane32_swap_b32_e32 v53, v55
	global_store_dwordx4 v[252:253], v[52:55], off offset:2048
	v_cndmask_b32_e64 v4, 0, v136, s[4:5]
	v_cndmask_b32_e64 v5, 0, v137, s[4:5]
	v_cndmask_b32_e64 v6, 0, v138, s[4:5]
	v_cndmask_b32_e64 v7, 0, v139, s[4:5]
	v_mfma_f32_32x32x16_bf16 v[16:31], v[108:111], v[48:51], v[16:31]
	v_cndmask_b32_e64 v54, 0, v140, s[4:5]
	v_cndmask_b32_e64 v55, 0, v141, s[4:5]
	v_cndmask_b32_e64 v56, 0, v142, s[4:5]
	v_cndmask_b32_e64 v57, 0, v143, s[4:5]
	v_cvt_pk_bf16_f32 v52, v4, v5
	v_cvt_pk_bf16_f32 v53, v6, v7
	v_cvt_pk_bf16_f32 v54, v54, v55
	v_cvt_pk_bf16_f32 v55, v56, v57
	v_cvt_pk_bf16_f32 v4, v8, v9
	v_cvt_pk_bf16_f32 v5, v10, v11
	v_mfma_f32_32x32x16_bf16 v[32:47], v[104:107], v[52:55], v[32:47]
	v_cndmask_b32_e64 v6, 0, v156, s[4:5]
	v_cndmask_b32_e64 v7, 0, v157, s[4:5]
	v_cndmask_b32_e64 v8, 0, v158, s[4:5]
	v_cndmask_b32_e64 v9, 0, v159, s[4:5]
	v_cndmask_b32_e64 v10, 0, v152, s[4:5]
	v_cndmask_b32_e64 v11, 0, v153, s[4:5]
	v_cndmask_b32_e64 v59, 0, v154, s[4:5]
	v_mfma_f32_32x32x16_bf16 v[16:31], v[100:103], v[52:55], v[16:31]
	v_cndmask_b32_e64 v60, 0, v155, s[4:5]
	v_cvt_pk_bf16_f32 v56, v6, v7
	v_cvt_pk_bf16_f32 v57, v8, v9
	v_cvt_pk_bf16_f32 v58, v10, v11
	v_cvt_pk_bf16_f32 v59, v59, v60
	v_cvt_pk_bf16_f32 v6, v12, v13
	v_cvt_pk_bf16_f32 v7, v14, v15
	v_mfma_f32_32x32x16_bf16 v[32:47], v[96:99], v[56:59], v[32:47]
	v_permlane32_swap_b32_e32 v4, v6
	v_permlane32_swap_b32_e32 v5, v7
	global_store_dwordx4 v[252:253], v[4:7], off offset:3072
	v_mfma_f32_32x32x16_bf16 v[16:31], v[92:95], v[56:59], v[16:31]
	s_nop 7
	v_cvt_pk_bf16_f32 v4, v32, v33
	v_cvt_pk_bf16_f32 v5, v34, v35
	v_cvt_pk_bf16_f32 v6, v36, v37
	v_cvt_pk_bf16_f32 v7, v38, v39
	s_nop 0
	v_permlane32_swap_b32_e32 v4, v6
	v_permlane32_swap_b32_e32 v5, v7
	s_and_saveexec_b64 s[66:67], s[4:5]
	s_cbranch_execz .LBB0_414
	v_add_co_u32_e32 v8, vcc, 0x8000, v208
	s_nop 1
	v_addc_co_u32_e32 v9, vcc, 0, v209, vcc
	global_store_dwordx4 v[8:9], v[4:7], off

.LBB0_714:
	s_or_b64 exec, exec, s[26:27]
	v_lshlrev_b32_e32 v153, 3, v144
	v_lshlrev_b32_e32 v134, 1, v153
	v_mov_b32_e32 v135, v133
	s_mov_b32 s100, s24
	s_mov_b32 s101, s25
	v_lshl_add_u64 v[16:17], s[24:25], 0, v[134:135]
	v_lshlrev_b32_e32 v18, 8, v132
	v_mov_b32_e32 v19, v133
	v_lshlrev_b32_e32 v84, 4, v132
	v_lshl_or_b32 v84, v144, 9, v84
	v_add_u32_e32 v85, 0x1000, v84
	v_add_u32_e32 v80, 0x2000, v84
	global_load_dwordx4 v[16:19], v84, s[100:101]
	s_nop 0
	v_add_u32_e32 v81, 0x3000, v84
	global_load_dwordx4 v[20:23], v80, s[100:101]
	v_add_u32_e32 v82, 0x4000, v84
	s_lshr_b32 s0, s2, 1
	s_nop 0
	v_add_u32_e32 v83, 0x5000, v84
	global_load_dwordx4 v[24:27], v82, s[100:101]
	global_load_dwordx4 v[64:67], v84, s[100:101] offset:1024
	global_load_dwordx4 v[68:71], v80, s[100:101] offset:1024
	global_load_dwordx4 v[76:79], v84, s[100:101] offset:2048
	global_load_dwordx4 v[72:75], v82, s[100:101] offset:1024
	v_add_u32_e32 v162, 0x6000, v84
	s_and_b32 s24, s0, 63
	s_nop 0
	v_add_u32_e32 v163, 0x7000, v84
	s_lshl_b32 s1, s2, 1
	s_lshl_b32 s0, s24, 6
	s_and_b32 s25, s1, 0x300
	s_lshl_b32 s26, s24, 8
	s_add_u32 s0, s22, s0
	s_addc_u32 s1, s23, 0
	s_waitcnt vmcnt(7)
	v_mfma_f32_32x32x16_bf16 v[0:15], v[128:131], v[124:127], v[0:15]
	v_lshlrev_b32_e32 v144, 2, v144
	v_mov_b32_e32 v135, v140
	s_waitcnt vmcnt(6)
	v_mfma_f32_32x32x16_bf16 v[48:63], v[16:19], v[96:99], 0
	s_waitcnt vmcnt(5)
	v_mfma_f32_32x32x16_bf16 v[32:47], v[20:23], v[96:99], 0
	s_waitcnt vmcnt(3)
	v_mfma_f32_32x32x16_bf16 v[48:63], v[64:67], v[100:103], v[48:63]
	global_load_dwordx4 v[64:67], v80, s[100:101] offset:2048
	s_waitcnt vmcnt(3)
	v_mfma_f32_32x32x16_bf16 v[32:47], v[68:71], v[100:103], v[32:47]
	global_load_dwordx4 v[68:71], v84, s[100:101] offset:3072
	s_waitcnt vmcnt(3)
	v_mfma_f32_32x32x16_bf16 v[48:63], v[76:79], v[104:107], v[48:63]
	global_load_dwordx4 v[76:79], v85, s[100:101]
	v_mfma_f32_32x32x16_bf16 v[16:31], v[24:27], v[96:99], 0
	s_waitcnt vmcnt(2)
	v_mfma_f32_32x32x16_bf16 v[32:47], v[64:67], v[104:107], v[32:47]
	global_load_dwordx4 v[64:67], v81, s[100:101]
	s_waitcnt vmcnt(2)
	v_mfma_f32_32x32x16_bf16 v[48:63], v[68:71], v[108:111], v[48:63]
	global_load_dwordx4 v[68:71], v85, s[100:101] offset:1024
	s_waitcnt vmcnt(2)
	v_mfma_f32_32x32x16_bf16 v[48:63], v[76:79], v[112:115], v[48:63]
	global_load_dwordx4 v[76:79], v85, s[100:101] offset:2048
	s_waitcnt vmcnt(1)
	v_mfma_f32_32x32x16_bf16 v[48:63], v[68:71], v[116:119], v[48:63]
	global_load_dwordx4 v[68:71], v85, s[100:101] offset:3072
	s_waitcnt vmcnt(1)
	v_mfma_f32_32x32x16_bf16 v[48:63], v[76:79], v[120:123], v[48:63]
	global_load_dwordx4 v[76:79], v82, s[100:101] offset:2048
	s_waitcnt vmcnt(1)
	v_mfma_f32_32x32x16_bf16 v[48:63], v[68:71], v[124:127], v[48:63]
	global_load_dwordx4 v[68:71], v83, s[100:101]
	v_mfma_f32_32x32x16_bf16 v[16:31], v[72:75], v[100:103], v[16:31]
	global_load_dwordx4 v[72:75], v80, s[100:101] offset:3072
	s_waitcnt vmcnt(0)
	v_mfma_f32_32x32x16_bf16 v[32:47], v[72:75], v[108:111], v[32:47]
	global_load_dwordx4 v[72:75], v81, s[100:101] offset:1024
	v_mfma_f32_32x32x16_bf16 v[32:47], v[64:67], v[112:115], v[32:47]
	global_load_dwordx4 v[64:67], v81, s[100:101] offset:2048
	s_waitcnt vmcnt(1)
	v_mfma_f32_32x32x16_bf16 v[32:47], v[72:75], v[116:119], v[32:47]
	global_load_dwordx4 v[72:75], v81, s[100:101] offset:3072
	s_waitcnt vmcnt(1)
	v_mfma_f32_32x32x16_bf16 v[32:47], v[64:67], v[120:123], v[32:47]
	global_load_dwordx4 v[64:67], v82, s[100:101] offset:3072
	s_waitcnt vmcnt(1)
	v_mfma_f32_32x32x16_bf16 v[32:47], v[72:75], v[124:127], v[32:47]
	global_load_dwordx4 v[72:75], v83, s[100:101] offset:1024
	v_mfma_f32_32x32x16_bf16 v[16:31], v[76:79], v[104:107], v[16:31]
	global_load_dwordx4 v[76:79], v83, s[100:101] offset:2048
	s_nop 0
	global_load_dwordx4 v[80:83], v83, s[100:101] offset:3072
	s_nop 0
	global_load_dwordx4 v[148:151], v163, s[100:101]
	global_load_dwordx4 v[154:157], v163, s[100:101] offset:1024
	global_load_dwordx4 v[158:161], v163, s[100:101] offset:2048
	s_waitcnt vmcnt(6)
	v_mfma_f32_32x32x16_bf16 v[16:31], v[64:67], v[108:111], v[16:31]
	global_load_dwordx4 v[64:67], v162, s[100:101]
	v_mfma_f32_32x32x16_bf16 v[16:31], v[68:71], v[112:115], v[16:31]
	global_load_dwordx4 v[68:71], v162, s[100:101] offset:1024
	s_waitcnt vmcnt(7)
	v_mfma_f32_32x32x16_bf16 v[16:31], v[72:75], v[116:119], v[16:31]
	global_load_dwordx4 v[72:75], v162, s[100:101] offset:2048
	s_waitcnt vmcnt(7)
	v_mfma_f32_32x32x16_bf16 v[16:31], v[76:79], v[120:123], v[16:31]
	global_load_dwordx4 v[76:79], v162, s[100:101] offset:3072
	s_nop 0
	global_load_dwordx4 v[162:165], v163, s[100:101] offset:3072
	s_waitcnt vmcnt(8)
	v_mfma_f32_32x32x16_bf16 v[16:31], v[80:83], v[124:127], v[16:31]
	s_waitcnt vmcnt(4)
	v_mfma_f32_32x32x16_bf16 v[80:95], v[64:67], v[96:99], 0
	v_mul_f32_e32 v64, 0x3fb8aa3b, v152
	v_exp_f32_e32 v142, v64
	s_nop 0
	v_pk_mul_f32 v[66:67], v[142:143], v[50:51] op_sel_hi:[0,1]
	v_pk_mul_f32 v[64:65], v[142:143], v[48:49] op_sel_hi:[0,1]
	s_waitcnt vmcnt(3)
	v_mfma_f32_32x32x16_bf16 v[80:95], v[68:71], v[100:103], v[80:95]
	v_mul_f32_e64 v50, v142, v34
	v_mul_f32_e64 v51, v142, v35
	v_mul_f32_e64 v48, v142, v32
	v_mul_f32_e64 v49, v142, v33
	v_mul_f32_e64 v34, v142, v18
	v_mul_f32_e64 v35, v142, v19
	v_pk_mul_f32 v[32:33], v[142:143], v[16:17] op_sel_hi:[0,1]
	v_pk_mul_f32 v[70:71], v[142:143], v[54:55] op_sel_hi:[0,1]
	v_pk_mul_f32 v[68:69], v[142:143], v[52:53] op_sel_hi:[0,1]
	v_pk_mul_f32 v[54:55], v[142:143], v[38:39] op_sel_hi:[0,1]
	v_pk_mul_f32 v[52:53], v[142:143], v[36:37] op_sel_hi:[0,1]
	v_pk_mul_f32 v[38:39], v[142:143], v[22:23] op_sel_hi:[0,1]
	v_pk_mul_f32 v[36:37], v[142:143], v[20:21] op_sel_hi:[0,1]
	s_waitcnt vmcnt(2)
	v_mfma_f32_32x32x16_bf16 v[80:95], v[72:75], v[104:107], v[80:95]
	v_mul_f32_e64 v74, v142, v58
	v_mul_f32_e64 v75, v142, v59
	v_mul_f32_e64 v72, v142, v56
	v_mul_f32_e64 v73, v142, v57
	v_mul_f32_e64 v58, v142, v42
	v_mul_f32_e64 v59, v142, v43
	v_pk_mul_f32 v[56:57], v[142:143], v[40:41] op_sel_hi:[0,1]
	v_pk_mul_f32 v[42:43], v[142:143], v[26:27] op_sel_hi:[0,1]
	v_pk_mul_f32 v[40:41], v[142:143], v[24:25] op_sel_hi:[0,1]
	s_waitcnt vmcnt(1)
	v_mfma_f32_32x32x16_bf16 v[80:95], v[76:79], v[108:111], v[80:95]
	v_mul_f32_e64 v78, v142, v62
	v_mul_f32_e64 v79, v142, v63
	v_mul_f32_e64 v76, v142, v60
	v_mul_f32_e64 v77, v142, v61
	v_mul_f32_e64 v62, v142, v46
	v_mul_f32_e64 v63, v142, v47
	v_pk_mul_f32 v[60:61], v[142:143], v[44:45] op_sel_hi:[0,1]
	v_pk_mul_f32 v[46:47], v[142:143], v[30:31] op_sel_hi:[0,1]
	v_pk_mul_f32 v[44:45], v[142:143], v[28:29] op_sel_hi:[0,1]
	v_mfma_f32_32x32x16_bf16 v[80:95], v[148:151], v[112:115], v[80:95]
	v_mfma_f32_32x32x16_bf16 v[80:95], v[154:157], v[116:119], v[80:95]
	v_mfma_f32_32x32x16_bf16 v[80:95], v[158:161], v[120:123], v[80:95]
	s_waitcnt vmcnt(0)
	v_mfma_f32_32x32x16_bf16 v[80:95], v[162:165], v[124:127], v[80:95]
	s_nop 11
	v_pk_mul_f32 v[18:19], v[142:143], v[82:83] op_sel_hi:[0,1]
	v_pk_mul_f32 v[16:17], v[142:143], v[80:81] op_sel_hi:[0,1]
	v_lshl_add_u64 v[80:81], s[0:1], 0, v[132:133]
	v_lshrrev_b32_e32 v82, 1, v146
	s_add_i32 s0, s71, s24
	v_lshlrev_b64 v[80:81], 10, v[80:81]
	v_and_b32_e32 v82, 16, v82
	s_ashr_i32 s1, s0, 31
	v_or3_b32 v80, v80, s25, v82
	s_lshl_b64 s[0:1], s[0:1], 14
	v_lshl_add_u64 v[146:147], v[80:81], 0, s[12:13]
	v_lshl_or_b32 v80, v132, 7, s0
	s_or_b32 s0, s20, s26
	s_add_u32 s0, s0, 0xc90040
	v_mov_b32_e32 v149, s1
	s_addc_u32 s1, s21, 0
	v_pk_mul_f32 v[30:31], v[142:143], v[94:95] op_sel_hi:[0,1]
	v_pk_mul_f32 v[28:29], v[142:143], v[92:93] op_sel_hi:[0,1]
	v_pk_mul_f32 v[26:27], v[142:143], v[90:91] op_sel_hi:[0,1]
	v_pk_mul_f32 v[24:25], v[142:143], v[88:89] op_sel_hi:[0,1]
	v_pk_mul_f32 v[22:23], v[142:143], v[86:87] op_sel_hi:[0,1]
	v_pk_mul_f32 v[20:21], v[142:143], v[84:85] op_sel_hi:[0,1]
	v_and_b32_e32 v84, 3, v132
	v_lshlrev_b32_e32 v84, 9, v84
	v_lshrrev_b32_e32 v85, 2, v132
	v_lshl_or_b32 v84, v85, 4, v84
	v_and_b32_e32 v85, 0xffffc000, v80
	v_or3_b32 v148, v85, v84, v153
	v_or_b32_e32 v150, s0, v82
	v_mov_b32_e32 v151, s1
	s_branch .LBB0_716

.LBB0_821:
	s_andn2_saveexec_b64 s[0:1], s[8:9]
	s_cbranch_execz .LBB0_841
	s_mov_b64 s[8:9], exec
	v_readlane_b32 s98, v255, 11
	s_nop 0
	s_cmp_lg_u32 s98, 0
	s_cbranch_scc1 .LBB0_838
	buffer_wbl2 sc1
	s_waitcnt lgkmcnt(0)
	s_waitcnt vmcnt(0)
	v_mbcnt_lo_u32_b32 v1, s8, 0
	v_mbcnt_hi_u32_b32 v1, s9, v1
	v_cmp_eq_u32_e32 vcc, 0, v1
	s_and_saveexec_b64 s[10:11], vcc
	s_cbranch_execz .LBB0_824
	s_bcnt1_i32_b64 s0, s[8:9]
	v_mov_b32_e32 v2, 0xfd2c000
	v_mov_b32_e32 v3, s0
	global_atomic_add v2, v2, v3, s[58:59] offset:1024 sc0

.LBB0_2048:
	s_andn2_saveexec_b64 s[2:3], s[6:7]
	s_cbranch_execz .LBB0_2068
	s_mov_b64 s[6:7], exec
	v_readlane_b32 s98, v255, 11
	s_nop 0
	s_cmp_lg_u32 s98, 0
	s_cbranch_scc1 .LBB0_2065
	buffer_wbl2 sc1
	s_waitcnt lgkmcnt(0)
	s_waitcnt vmcnt(0)
	v_mbcnt_lo_u32_b32 v1, s6, 0
	v_mbcnt_hi_u32_b32 v1, s7, v1
	v_cmp_eq_u32_e32 vcc, 0, v1
	s_and_saveexec_b64 s[8:9], vcc
	s_cbranch_execz .LBB0_2051
	s_bcnt1_i32_b64 s2, s[6:7]
	v_mov_b32_e32 v2, 0xfd2c000
	v_mov_b32_e32 v3, s2
	global_atomic_add v2, v2, v3, s[58:59] offset:1024 sc0
